# split-K partial-slab stores (EpiPart, 4 sample-panel GEMMs) made write-through (sc1) so the following grid-barrier L2 writeback is cheap
# baseline (speedup 1.0000x reference)
;   __device__ __forceinline__ void operator()(const f32x4 (&acc)[2][2][4][2], const pg8::Unit& u, int wr, int wc, int fr, int fq) const {
;     float* pb = part + ((size_t)(u.k0 >> 8) * 256 + wr * 64 + fr) * ld + u.pn * 256 + wc * 32 + 4 * fq;
; #pragma unroll
;     for (int ai = 0; ai < 2; ++ai)
; #pragma unroll
;       for (int m = 0; m < 4; ++m)
; #pragma unroll
;         for (int bj = 0; bj < 2; ++bj)
; #pragma unroll
;           for (int n = 0; n < 2; ++n) *(f32x4*)(pb + (size_t)(ai * 128 + m * 16) * ld + bj * 128 + n * 16) = acc[ai][bj][m][n];
.LBB0_299:
	s_ashr_i32 s36, s16, 8
	s_ashr_i32 s37, s36, 31
	s_lshl_b64 s[36:37], s[36:37], 21
	v_lshl_add_u64 v[146:147], v[134:135], 0, s[36:37]
	s_lshl_b32 s36, s48, 8
	s_ashr_i32 s37, s36, 31
	v_lshl_add_u64 v[146:147], s[36:37], 2, v[146:147]
	v_lshl_add_u64 v[146:147], v[146:147], 0, s[4:5]
	v_lshl_add_u64 v[146:147], v[146:147], 0, v[132:133]
	s_mov_b32 s16, 0x20000
	global_store_dwordx4 v[146:147], v[124:127], off sc1
	global_store_dwordx4 v[146:147], v[120:123], off offset:64 sc1
	global_store_dwordx4 v[146:147], v[104:107], off offset:512 sc1
	global_store_dwordx4 v[146:147], v[96:99], off offset:576 sc1
	v_readlane_b32 s58, v246, 23
	v_readlane_b32 s59, v246, 24
	v_add_co_u32_e32 v96, vcc, s16, v146
	s_mov_b32 s16, 0x40000
	s_nop 0
	v_addc_co_u32_e32 v97, vcc, 0, v147, vcc
	global_store_dwordx4 v[96:97], v[116:119], off sc1
	global_store_dwordx4 v[96:97], v[112:115], off offset:64 sc1
	global_store_dwordx4 v[96:97], v[88:91], off offset:512 sc1
	global_store_dwordx4 v[96:97], v[80:83], off offset:576 sc1
	s_nop 1
	v_add_co_u32_e32 v80, vcc, s16, v146
	s_mov_b32 s16, 0x60000
	s_nop 0
	v_addc_co_u32_e32 v81, vcc, 0, v147, vcc
	global_store_dwordx4 v[80:81], v[108:111], off sc1
	global_store_dwordx4 v[80:81], v[100:103], off offset:64 sc1
	global_store_dwordx4 v[80:81], v[76:79], off offset:512 sc1
	global_store_dwordx4 v[80:81], v[72:75], off offset:576 sc1
	s_nop 1
	v_add_co_u32_e32 v72, vcc, s16, v146
	s_mov_b32 s16, 0x100000
	s_nop 0
	v_addc_co_u32_e32 v73, vcc, 0, v147, vcc
	global_store_dwordx4 v[72:73], v[92:95], off sc1
	global_store_dwordx4 v[72:73], v[84:87], off offset:64 sc1
	global_store_dwordx4 v[72:73], v[68:71], off offset:512 sc1
	global_store_dwordx4 v[72:73], v[64:67], off offset:576 sc1
	s_nop 1
	v_add_co_u32_e32 v64, vcc, s16, v146
	s_mov_b32 s16, 0x120000
	s_nop 0
	v_addc_co_u32_e32 v65, vcc, 0, v147, vcc
	global_store_dwordx4 v[64:65], v[60:63], off sc1
	global_store_dwordx4 v[64:65], v[56:59], off offset:64 sc1
	global_store_dwordx4 v[64:65], v[44:47], off offset:512 sc1
	global_store_dwordx4 v[64:65], v[36:39], off offset:576 sc1
	s_nop 1
	v_add_co_u32_e32 v36, vcc, s16, v146
	s_nop 1
	v_addc_co_u32_e32 v37, vcc, 0, v147, vcc
	global_store_dwordx4 v[36:37], v[52:55], off sc1
	global_store_dwordx4 v[36:37], v[48:51], off offset:64 sc1
	global_store_dwordx4 v[36:37], v[28:31], off offset:512 sc1
	global_store_dwordx4 v[36:37], v[20:23], off offset:576 sc1
	s_nop 1
	v_add_co_u32_e32 v20, vcc, 0x140000, v146
	s_nop 1
	v_addc_co_u32_e32 v21, vcc, 0, v147, vcc
	global_store_dwordx4 v[20:21], v[40:43], off sc1
	global_store_dwordx4 v[20:21], v[32:35], off offset:64 sc1
	global_store_dwordx4 v[20:21], v[12:15], off offset:512 sc1
	global_store_dwordx4 v[20:21], v[8:11], off offset:576 sc1
	s_nop 1
	v_add_co_u32_e32 v8, vcc, 0x160000, v146
	s_nop 1
	v_addc_co_u32_e32 v9, vcc, 0, v147, vcc
	s_and_b64 vcc, exec, s[0:1]
	s_mov_b64 s[0:1], -1
	global_store_dwordx4 v[8:9], v[24:27], off sc1
	global_store_dwordx4 v[8:9], v[16:19], off offset:64 sc1
	global_store_dwordx4 v[8:9], v[4:7], off offset:512 sc1
	global_store_dwordx4 v[8:9], v[0:3], off offset:576 sc1
	s_cbranch_vccnz .LBB0_290
	s_andn2_b64 vcc, exec, s[6:7]
	s_cbranch_vccnz .LBB0_289
	s_barrier
	s_branch .LBB0_289

;   __device__ __forceinline__ void operator()(const f32x4 (&acc)[2][2][4][2], const pg8::Unit& u, int wr, int wc, int fr, int fq) const {
;     float* pb = part + ((size_t)(u.k0 >> 8) * 256 + wr * 64 + fr) * ld + u.pn * 256 + wc * 32 + 4 * fq;
; #pragma unroll
;     for (int ai = 0; ai < 2; ++ai)
; #pragma unroll
;       for (int m = 0; m < 4; ++m)
; #pragma unroll
;         for (int bj = 0; bj < 2; ++bj)
; #pragma unroll
;           for (int n = 0; n < 2; ++n) *(f32x4*)(pb + (size_t)(ai * 128 + m * 16) * ld + bj * 128 + n * 16) = acc[ai][bj][m][n];
.LBB0_521:
	s_ashr_i32 s16, s10, 8
	s_ashr_i32 s17, s16, 31
	s_lshl_b64 s[16:17], s[16:17], 22
	v_lshl_add_u64 v[142:143], v[134:135], 0, s[16:17]
	s_lshl_b32 s16, s8, 8
	s_ashr_i32 s17, s16, 31
	v_lshl_add_u64 v[142:143], s[16:17], 2, v[142:143]
	v_lshl_add_u64 v[142:143], v[142:143], 0, s[4:5]
	v_lshl_add_u64 v[142:143], v[142:143], 0, v[132:133]
	s_mov_b32 s8, 0x40000
	global_store_dwordx4 v[142:143], v[124:127], off sc1
	global_store_dwordx4 v[142:143], v[120:123], off offset:64 sc1
	global_store_dwordx4 v[142:143], v[104:107], off offset:512 sc1
	global_store_dwordx4 v[142:143], v[96:99], off offset:576 sc1
	s_nop 1
	v_add_co_u32_e32 v96, vcc, s8, v142
	s_mov_b32 s8, 0x80000
	s_nop 0
	v_addc_co_u32_e32 v97, vcc, 0, v143, vcc
	global_store_dwordx4 v[96:97], v[116:119], off sc1
	global_store_dwordx4 v[96:97], v[112:115], off offset:64 sc1
	global_store_dwordx4 v[96:97], v[88:91], off offset:512 sc1
	global_store_dwordx4 v[96:97], v[80:83], off offset:576 sc1
	s_nop 1
	v_add_co_u32_e32 v80, vcc, s8, v142
	s_mov_b32 s8, 0xc0000
	s_nop 0
	v_addc_co_u32_e32 v81, vcc, 0, v143, vcc
	global_store_dwordx4 v[80:81], v[108:111], off sc1
	global_store_dwordx4 v[80:81], v[100:103], off offset:64 sc1
	global_store_dwordx4 v[80:81], v[76:79], off offset:512 sc1
	global_store_dwordx4 v[80:81], v[72:75], off offset:576 sc1
	s_nop 1
	v_add_co_u32_e32 v72, vcc, s8, v142
	s_mov_b32 s8, 0x200000
	s_nop 0
	v_addc_co_u32_e32 v73, vcc, 0, v143, vcc
	global_store_dwordx4 v[72:73], v[92:95], off sc1
	global_store_dwordx4 v[72:73], v[84:87], off offset:64 sc1
	global_store_dwordx4 v[72:73], v[68:71], off offset:512 sc1
	global_store_dwordx4 v[72:73], v[64:67], off offset:576 sc1
	s_nop 1
	v_add_co_u32_e32 v64, vcc, s8, v142
	s_mov_b32 s8, 0x240000
	s_nop 0
	v_addc_co_u32_e32 v65, vcc, 0, v143, vcc
	global_store_dwordx4 v[64:65], v[60:63], off sc1
	global_store_dwordx4 v[64:65], v[56:59], off offset:64 sc1
	global_store_dwordx4 v[64:65], v[44:47], off offset:512 sc1
	global_store_dwordx4 v[64:65], v[36:39], off offset:576 sc1
	s_nop 1
	v_add_co_u32_e32 v36, vcc, s8, v142
	s_nop 1
	v_addc_co_u32_e32 v37, vcc, 0, v143, vcc
	global_store_dwordx4 v[36:37], v[52:55], off sc1
	global_store_dwordx4 v[36:37], v[48:51], off offset:64 sc1
	global_store_dwordx4 v[36:37], v[28:31], off offset:512 sc1
	global_store_dwordx4 v[36:37], v[20:23], off offset:576 sc1
	s_nop 1
	v_add_co_u32_e32 v20, vcc, 0x280000, v142
	s_nop 1
	v_addc_co_u32_e32 v21, vcc, 0, v143, vcc
	global_store_dwordx4 v[20:21], v[40:43], off sc1
	global_store_dwordx4 v[20:21], v[32:35], off offset:64 sc1
	global_store_dwordx4 v[20:21], v[12:15], off offset:512 sc1
	global_store_dwordx4 v[20:21], v[8:11], off offset:576 sc1
	s_nop 1
	v_add_co_u32_e32 v8, vcc, 0x2c0000, v142
	s_nop 1
	v_addc_co_u32_e32 v9, vcc, 0, v143, vcc
	s_and_b64 vcc, exec, s[0:1]
	s_mov_b64 s[0:1], -1
	global_store_dwordx4 v[8:9], v[24:27], off sc1
	global_store_dwordx4 v[8:9], v[16:19], off offset:64 sc1
	global_store_dwordx4 v[8:9], v[4:7], off offset:512 sc1
	global_store_dwordx4 v[8:9], v[0:3], off offset:576 sc1
	s_cbranch_vccnz .LBB0_512
	s_andn2_b64 vcc, exec, s[6:7]
	s_cbranch_vccnz .LBB0_511
	s_barrier
	s_branch .LBB0_511

;   __device__ __forceinline__ void operator()(const f32x4 (&acc)[2][2][4][2], const pg8::Unit& u, int wr, int wc, int fr, int fq) const {
;     float* pb = part + ((size_t)(u.k0 >> 8) * 256 + wr * 64 + fr) * ld + u.pn * 256 + wc * 32 + 4 * fq;
; #pragma unroll
;     for (int ai = 0; ai < 2; ++ai)
; #pragma unroll
;       for (int m = 0; m < 4; ++m)
; #pragma unroll
;         for (int bj = 0; bj < 2; ++bj)
; #pragma unroll
;           for (int n = 0; n < 2; ++n) *(f32x4*)(pb + (size_t)(ai * 128 + m * 16) * ld + bj * 128 + n * 16) = acc[ai][bj][m][n];
.LBB0_1115:
	s_ashr_i32 s14, s12, 8
	s_ashr_i32 s15, s14, 31
	s_lshl_b64 s[14:15], s[14:15], 21
	v_lshl_add_u64 v[142:143], v[134:135], 0, s[14:15]
	s_lshl_b32 s14, s10, 8
	s_ashr_i32 s15, s14, 31
	v_lshl_add_u64 v[142:143], s[14:15], 2, v[142:143]
	v_lshl_add_u64 v[142:143], v[142:143], 0, s[4:5]
	v_lshl_add_u64 v[142:143], v[142:143], 0, v[132:133]
	s_mov_b32 s10, 0x20000
	global_store_dwordx4 v[142:143], v[124:127], off sc1
	global_store_dwordx4 v[142:143], v[120:123], off offset:64 sc1
	global_store_dwordx4 v[142:143], v[104:107], off offset:512 sc1
	global_store_dwordx4 v[142:143], v[96:99], off offset:576 sc1
	s_nop 1
	v_add_co_u32_e32 v96, vcc, s10, v142
	s_mov_b32 s10, 0x40000
	s_nop 0
	v_addc_co_u32_e32 v97, vcc, 0, v143, vcc
	global_store_dwordx4 v[96:97], v[116:119], off sc1
	global_store_dwordx4 v[96:97], v[112:115], off offset:64 sc1
	global_store_dwordx4 v[96:97], v[88:91], off offset:512 sc1
	global_store_dwordx4 v[96:97], v[80:83], off offset:576 sc1
	s_nop 1
	v_add_co_u32_e32 v80, vcc, s10, v142
	s_mov_b32 s10, 0x60000
	s_nop 0
	v_addc_co_u32_e32 v81, vcc, 0, v143, vcc
	global_store_dwordx4 v[80:81], v[108:111], off sc1
	global_store_dwordx4 v[80:81], v[100:103], off offset:64 sc1
	global_store_dwordx4 v[80:81], v[76:79], off offset:512 sc1
	global_store_dwordx4 v[80:81], v[72:75], off offset:576 sc1
	s_nop 1
	v_add_co_u32_e32 v72, vcc, s10, v142
	s_mov_b32 s10, 0x100000
	s_nop 0
	v_addc_co_u32_e32 v73, vcc, 0, v143, vcc
	global_store_dwordx4 v[72:73], v[92:95], off sc1
	global_store_dwordx4 v[72:73], v[84:87], off offset:64 sc1
	global_store_dwordx4 v[72:73], v[68:71], off offset:512 sc1
	global_store_dwordx4 v[72:73], v[64:67], off offset:576 sc1
	s_nop 1
	v_add_co_u32_e32 v64, vcc, s10, v142
	s_mov_b32 s10, 0x120000
	s_nop 0
	v_addc_co_u32_e32 v65, vcc, 0, v143, vcc
	global_store_dwordx4 v[64:65], v[60:63], off sc1
	global_store_dwordx4 v[64:65], v[56:59], off offset:64 sc1
	global_store_dwordx4 v[64:65], v[44:47], off offset:512 sc1
	global_store_dwordx4 v[64:65], v[36:39], off offset:576 sc1
	s_nop 1
	v_add_co_u32_e32 v36, vcc, s10, v142
	s_nop 1
	v_addc_co_u32_e32 v37, vcc, 0, v143, vcc
	global_store_dwordx4 v[36:37], v[52:55], off sc1
	global_store_dwordx4 v[36:37], v[48:51], off offset:64 sc1
	global_store_dwordx4 v[36:37], v[24:27], off offset:512 sc1
	global_store_dwordx4 v[36:37], v[16:19], off offset:576 sc1
	s_nop 1
	v_add_co_u32_e32 v16, vcc, 0x140000, v142
	s_nop 1
	v_addc_co_u32_e32 v17, vcc, 0, v143, vcc
	global_store_dwordx4 v[16:17], v[40:43], off sc1
	global_store_dwordx4 v[16:17], v[32:35], off offset:64 sc1
	global_store_dwordx4 v[16:17], v[12:15], off offset:512 sc1
	global_store_dwordx4 v[16:17], v[8:11], off offset:576 sc1
	s_nop 1
	v_add_co_u32_e32 v8, vcc, 0x160000, v142
	s_nop 1
	v_addc_co_u32_e32 v9, vcc, 0, v143, vcc
	s_and_b64 vcc, exec, s[0:1]
	s_mov_b64 s[0:1], -1
	global_store_dwordx4 v[8:9], v[28:31], off sc1
	global_store_dwordx4 v[8:9], v[20:23], off offset:64 sc1
	global_store_dwordx4 v[8:9], v[4:7], off offset:512 sc1
	global_store_dwordx4 v[8:9], v[0:3], off offset:576 sc1
	s_cbranch_vccnz .LBB0_1106
	s_andn2_b64 vcc, exec, s[6:7]
	s_cbranch_vccnz .LBB0_1105
	s_barrier
	s_branch .LBB0_1105

;   __device__ __forceinline__ void operator()(const f32x4 (&acc)[2][2][4][2], const pg8::Unit& u, int wr, int wc, int fr, int fq) const {
;     float* pb = part + ((size_t)(u.k0 >> 8) * 256 + wr * 64 + fr) * ld + u.pn * 256 + wc * 32 + 4 * fq;
; #pragma unroll
;     for (int ai = 0; ai < 2; ++ai)
; #pragma unroll
;       for (int m = 0; m < 4; ++m)
; #pragma unroll
;         for (int bj = 0; bj < 2; ++bj)
; #pragma unroll
;           for (int n = 0; n < 2; ++n) *(f32x4*)(pb + (size_t)(ai * 128 + m * 16) * ld + bj * 128 + n * 16) = acc[ai][bj][m][n];
.LBB0_1351:
	s_ashr_i32 s20, s10, 8
	s_ashr_i32 s21, s20, 31
	s_lshl_b64 s[20:21], s[20:21], 21
	v_lshl_add_u64 v[144:145], v[134:135], 0, s[20:21]
	s_lshl_b32 s20, s41, 8
	s_ashr_i32 s21, s20, 31
	v_lshl_add_u64 v[144:145], s[20:21], 2, v[144:145]
	v_lshl_add_u64 v[144:145], v[144:145], 0, s[4:5]
	v_lshl_add_u64 v[144:145], v[144:145], 0, v[132:133]
	global_store_dwordx4 v[144:145], v[124:127], off sc1
	global_store_dwordx4 v[144:145], v[120:123], off offset:64 sc1
	global_store_dwordx4 v[144:145], v[104:107], off offset:512 sc1
	global_store_dwordx4 v[144:145], v[96:99], off offset:576 sc1
	s_nop 1
	v_add_co_u32_e32 v96, vcc, s46, v144
	s_nop 1
	v_addc_co_u32_e32 v97, vcc, 0, v145, vcc
	global_store_dwordx4 v[96:97], v[116:119], off sc1
	global_store_dwordx4 v[96:97], v[112:115], off offset:64 sc1
	global_store_dwordx4 v[96:97], v[88:91], off offset:512 sc1
	global_store_dwordx4 v[96:97], v[80:83], off offset:576 sc1
	s_nop 1
	v_add_co_u32_e32 v80, vcc, s47, v144
	s_nop 1
	v_addc_co_u32_e32 v81, vcc, 0, v145, vcc
	global_store_dwordx4 v[80:81], v[108:111], off sc1
	global_store_dwordx4 v[80:81], v[100:103], off offset:64 sc1
	global_store_dwordx4 v[80:81], v[76:79], off offset:512 sc1
	global_store_dwordx4 v[80:81], v[72:75], off offset:576 sc1
	s_nop 1
	v_add_co_u32_e32 v72, vcc, s48, v144
	s_nop 1
	v_addc_co_u32_e32 v73, vcc, 0, v145, vcc
	global_store_dwordx4 v[72:73], v[92:95], off sc1
	global_store_dwordx4 v[72:73], v[84:87], off offset:64 sc1
	global_store_dwordx4 v[72:73], v[68:71], off offset:512 sc1
	global_store_dwordx4 v[72:73], v[64:67], off offset:576 sc1
	s_nop 1
	v_add_co_u32_e32 v64, vcc, s49, v144
	s_nop 1
	v_addc_co_u32_e32 v65, vcc, 0, v145, vcc
	global_store_dwordx4 v[64:65], v[60:63], off sc1
	global_store_dwordx4 v[64:65], v[56:59], off offset:64 sc1
	global_store_dwordx4 v[64:65], v[40:43], off offset:512 sc1
	global_store_dwordx4 v[64:65], v[32:35], off offset:576 sc1
	s_nop 1
	v_add_co_u32_e32 v32, vcc, s50, v144
	s_nop 1
	v_addc_co_u32_e32 v33, vcc, 0, v145, vcc
	global_store_dwordx4 v[32:33], v[52:55], off sc1
	global_store_dwordx4 v[32:33], v[48:51], off offset:64 sc1
	global_store_dwordx4 v[32:33], v[24:27], off offset:512 sc1
	global_store_dwordx4 v[32:33], v[16:19], off offset:576 sc1
	s_nop 1
	v_add_co_u32_e32 v16, vcc, 0x140000, v144
	s_nop 1
	v_addc_co_u32_e32 v17, vcc, 0, v145, vcc
	global_store_dwordx4 v[16:17], v[44:47], off sc1
	global_store_dwordx4 v[16:17], v[36:39], off offset:64 sc1
	global_store_dwordx4 v[16:17], v[12:15], off offset:512 sc1
	global_store_dwordx4 v[16:17], v[8:11], off offset:576 sc1
	s_nop 1
	v_add_co_u32_e32 v8, vcc, 0x160000, v144
	s_nop 1
	v_addc_co_u32_e32 v9, vcc, 0, v145, vcc
	s_and_b64 vcc, exec, s[0:1]
	s_mov_b64 s[0:1], -1
	global_store_dwordx4 v[8:9], v[28:31], off sc1
	global_store_dwordx4 v[8:9], v[20:23], off offset:64 sc1
	global_store_dwordx4 v[8:9], v[4:7], off offset:512 sc1
	global_store_dwordx4 v[8:9], v[0:3], off offset:576 sc1
	s_cbranch_vccnz .LBB0_1342
	s_andn2_b64 vcc, exec, s[6:7]
	s_cbranch_vccnz .LBB0_1341
	s_barrier
	s_branch .LBB0_1341
